# K-loop head: first-tile flag computed on the scalar unit after the LDS fragment reads are issued (VALU add + readfirstlane chain removed)
# baseline (speedup 1.0000x reference)
; template <class Epi, class Sched, bool ALIGN_EPI = false, bool SP2 = false>
; __device__ __forceinline__ void gemm_phase(PG8_LAS unsigned char* lds, const Gemm g, const Sched& S, const Epi& E, const int wave_id) {
;     ...
;         const char* nA = has_next ? (const char*)g.A + (size_t)nxt.pm * tstep : cA; const char* nB = has_next ? (const char*)g.Bt + (size_t)nxt.pn * tstep : cB;
;         for (int t = 0; t < nt; t += 2) {
;             const bool last = (t == nt - 2);
;             const char* a1 = cA + (size_t)(t + 1) * kstep;
;             const char* a2 = last ? nA : cA + (size_t)(t + 2) * kstep; const char* b2 = last ? nB : cB + (size_t)(t + 2) * kstep;
;             const char* a3 = a2 + kstep; const char* b3 = b2 + kstep;
;             if (last && has_next) S.a_ready(nxt);
;             if constexpr (SP2) {
;             int tz_ = __builtin_amdgcn_readfirstlane(t | (ui > 0 ? 0 : 1)); asm volatile("" : "+s"(tz_));
;     ...
;         for (int a = 0; a < 2; ++a)
; #pragma unroll
;             for (int b = 0; b < 2; ++b)
; #pragma unroll
;                 for (int m = 0; m < 4; ++m)
; #pragma unroll
;                     for (int n = 0; n < 2; ++n) acc[a][b][m][n] = (f32x4){0.f, 0.f, 0.f, 0.f};
.LBB0_156:
	s_ashr_i32 s13, s12, 31
	s_lshl_b64 s[14:15], s[12:13], 19
	s_add_u32 s14, s35, s14
	s_addc_u32 s15, s36, s15
	s_and_b64 s[16:17], s[4:5], exec
	s_cselect_b32 s13, s15, s21
	s_cselect_b32 s68, s14, s20
	s_ashr_i32 s11, s10, 31
	s_lshl_b64 s[16:17], s[10:11], 19
	s_add_u32 s16, s37, s16
	s_addc_u32 s17, s38, s17
	s_and_b64 s[26:27], s[4:5], exec
	s_cselect_b32 s11, s17, s23
	s_cselect_b32 s69, s16, s22
	s_cmp_eq_u32 s24, 0
	s_cselect_b64 s[24:25], -1, 0
	s_add_u32 s74, s22, 0x100
	s_addc_u32 s75, s23, 0
	s_add_u32 s22, s20, 0x40080
	s_addc_u32 s23, s21, 0
	v_mov_b32_e32 v2, 0
	v_mov_b64_e32 v[196:197], 0x400
	v_cndmask_b32_e64 v250, 0, 1, s[24:25]
	s_and_b32 s101, s24, 1
	v_lshl_add_u64 v[222:223], s[22:23], 0, v[218:219]
	v_lshl_add_u64 v[224:225], s[22:23], 0, v[220:221]
	s_mov_b32 s76, -2
	s_mov_b64 s[22:23], 0
	v_mov_b32_e32 v3, v2
	v_mov_b64_e32 v[4:5], 0
	v_mov_b64_e32 v[6:7], 0
	v_mov_b64_e32 v[8:9], 0
	v_mov_b64_e32 v[10:11], 0
	v_mov_b64_e32 v[12:13], 0
	v_mov_b64_e32 v[14:15], 0
	v_mov_b64_e32 v[16:17], 0
	v_mov_b64_e32 v[18:19], 0
	v_mov_b64_e32 v[20:21], 0
	v_mov_b64_e32 v[22:23], 0
	v_mov_b64_e32 v[24:25], 0
	v_mov_b64_e32 v[26:27], 0
	v_mov_b64_e32 v[28:29], 0
	v_mov_b64_e32 v[30:31], 0
	v_mov_b64_e32 v[32:33], 0
	v_mov_b64_e32 v[34:35], 0
	v_mov_b64_e32 v[36:37], 0
	v_mov_b64_e32 v[38:39], 0
	v_mov_b64_e32 v[40:41], 0
	v_mov_b64_e32 v[42:43], 0
	v_mov_b64_e32 v[44:45], 0
	v_mov_b64_e32 v[46:47], 0
	v_mov_b64_e32 v[48:49], 0
	v_mov_b64_e32 v[50:51], 0
	v_mov_b64_e32 v[52:53], 0
	v_mov_b64_e32 v[54:55], 0
	v_mov_b64_e32 v[56:57], 0
	v_mov_b64_e32 v[58:59], 0
	v_mov_b64_e32 v[60:61], 0
	v_mov_b64_e32 v[62:63], 0
	v_mov_b64_e32 v[64:65], 0
	v_mov_b64_e32 v[66:67], 0
	v_mov_b64_e32 v[68:69], 0
	v_mov_b64_e32 v[70:71], 0
	v_mov_b64_e32 v[72:73], 0
	v_mov_b64_e32 v[74:75], 0
	v_mov_b64_e32 v[76:77], 0
	v_mov_b64_e32 v[78:79], 0
	v_mov_b64_e32 v[80:81], 0
	v_mov_b64_e32 v[82:83], 0
	v_mov_b64_e32 v[84:85], 0
	v_mov_b64_e32 v[86:87], 0
	v_mov_b64_e32 v[88:89], 0
	v_mov_b64_e32 v[90:91], 0
	v_mov_b64_e32 v[92:93], 0
	v_mov_b64_e32 v[94:95], 0
	v_mov_b64_e32 v[96:97], 0
	v_mov_b64_e32 v[98:99], 0
	v_mov_b64_e32 v[100:101], 0
	v_mov_b64_e32 v[102:103], 0
	v_mov_b64_e32 v[104:105], 0
	v_mov_b64_e32 v[106:107], 0
	v_mov_b64_e32 v[108:109], 0
	v_mov_b64_e32 v[110:111], 0
	v_mov_b64_e32 v[112:113], 0
	v_mov_b64_e32 v[114:115], 0
	v_mov_b64_e32 v[116:117], 0
	v_mov_b64_e32 v[118:119], 0
	v_mov_b64_e32 v[120:121], 0
	v_mov_b64_e32 v[122:123], 0
	v_mov_b64_e32 v[124:125], 0
	v_mov_b64_e32 v[126:127], 0
	v_mov_b64_e32 v[128:129], 0
	s_branch .LBB0_158

; #define PG8_STAGE(bufoff, gbase, voff) do { _Pragma("unroll") for (int _i = 0; _i < 2; ++_i) \
;         __builtin_amdgcn_global_load_lds((const unsigned*)((const char*)(gbase) + (voff)[_i]), (PG8_LAS unsigned*)(lds + (bufoff) + ldsw + _i * 8192), 16, 0, 0); } while (0)
; #define PG8_LDA(dst, b, h) do { _Pragma("unroll") for (int m = 0; m < 4; ++m) _Pragma("unroll") for (int k = 0; k < 2; ++k) dst[m][k] = *(const PG8_LAS bf16x8*)(lds + PG8_SA(b, h) + aoff + m * 2048 + k * 1024); } while (0)
; #define PG8_LDB(dst, b, h) do { _Pragma("unroll") for (int n = 0; n < 2; ++n) _Pragma("unroll") for (int k = 0; k < 2; ++k) dst[n][k] = *(const PG8_LAS bf16x8*)(lds + PG8_SB(b, h) + boff + n * 2048 + k * 1024); } while (0)
; #define PG8_MMA(ai, bj, At, Bt) do { __builtin_amdgcn_s_setprio(1); _Pragma("unroll") for (int m = 0; m < 4; ++m) _Pragma("unroll") for (int n = 0; n < 2; ++n) _Pragma("unroll") for (int k = 0; k < 2; ++k) \
;         acc[ai][bj][m][n] = __builtin_amdgcn_mfma_f32_16x16x32_bf16(Bt[n][k], At[m][k], acc[ai][bj][m][n], 0, 0, 0); __builtin_amdgcn_s_setprio(0); } while (0)
; #define PG8_WAIT_V(n) asm volatile("s_waitcnt vmcnt(" #n ")" ::: "memory")
; #define PG8_WAIT_VN(n) asm volatile("s_waitcnt vmcnt(%0)" :: "n"(n) : "memory")
; #define PG8_WAIT_L(n) asm volatile("s_waitcnt lgkmcnt(" #n ")" ::: "memory")
; #define PG8_BAR __builtin_amdgcn_s_barrier()
; #define PG8_SCHED __builtin_amdgcn_sched_barrier(0)
; template <class Epi, class Sched, bool ALIGN_EPI = false, bool SP2 = false>
; __device__ __forceinline__ void gemm_phase(PG8_LAS unsigned char* lds, const Gemm g, const Sched& S, const Epi& E, const int wave_id) {
;     ...
;             int tz_ = __builtin_amdgcn_readfirstlane(t | (ui > 0 ? 0 : 1)); asm volatile("" : "+s"(tz_));
;             const bool strict = !(Epi::NS > 0 && tz_ == 0);
;             PG8_LDB(B0, 0, 0); PG8_LDB(B1, 0, 1); PG8_SCHED; PG8_LDA(At, 0, 0); PG8_STAGE(PG8_SA(1, 1), a1 + hstep, voffA);
;             PG8_WAIT_VN(8 + Epi::NS); if (strict) PG8_WAIT_V(8); PG8_WAIT_L(0); PG8_BAR; PG8_MMA(0, 0, At, B0); PG8_MMA(0, 1, At, B1); PG8_BAR; PG8_SCHED;
.LBB0_158:
	ds_read_b128 v[146:149], v247
	ds_read_b128 v[150:153], v247 offset:1024
	ds_read_b128 v[154:157], v247 offset:2048
	ds_read_b128 v[158:161], v247 offset:3072
	ds_read_b128 v[130:133], v248
	ds_read_b128 v[134:137], v248 offset:1024
	ds_read_b128 v[138:141], v248 offset:2048
	ds_read_b128 v[142:145], v248 offset:3072
	v_lshl_add_u64 v[194:195], v[224:225], 0, s[22:23]
	s_add_i32 m0, s41, 0xc000
	ds_read_b128 v[186:189], v249
	ds_read_b128 v[190:193], v249 offset:1024
	ds_read_b128 v[178:181], v249 offset:2048
	ds_read_b128 v[182:185], v249 offset:3072
	ds_read_b128 v[170:173], v249 offset:4096
	ds_read_b128 v[174:177], v249 offset:5120
	ds_read_b128 v[162:165], v249 offset:6144
	ds_read_b128 v[166:169], v249 offset:7168
	global_load_lds_dwordx4 v[194:195], off
	v_lshl_add_u64 v[194:195], v[222:223], 0, s[22:23]
	s_add_i32 m0, s41, 0xe000
	s_add_i32 s24, s76, s101
	s_add_i32 s24, s24, 2
	s_mov_b32 s100, s24
	s_cmp_lg_u32 s24, 0
	global_load_lds_dwordx4 v[194:195], off
	s_waitcnt vmcnt(16)
	s_cselect_b64 s[28:29], -1, 0
	s_cmp_eq_u32 s24, 0
	s_cbranch_scc1 .LBB0_160
	s_waitcnt vmcnt(8)

; template <class Epi, class Sched, bool ALIGN_EPI = false, bool SP2 = false>
; __device__ __forceinline__ void gemm_phase(PG8_LAS unsigned char* lds, const Gemm g, const Sched& S, const Epi& E, const int wave_id) {
;     ...
;         const char* nA = has_next ? (const char*)g.A + (size_t)nxt.pm * tstep : cA; const char* nB = has_next ? (const char*)g.Bt + (size_t)nxt.pn * tstep : cB;
;         for (int t = 0; t < nt; t += 2) {
;             const bool last = (t == nt - 2);
;             const char* a1 = cA + (size_t)(t + 1) * kstep;
;             const char* a2 = last ? nA : cA + (size_t)(t + 2) * kstep; const char* b2 = last ? nB : cB + (size_t)(t + 2) * kstep;
;             const char* a3 = a2 + kstep; const char* b3 = b2 + kstep;
;             if (last && has_next) S.a_ready(nxt);
;             if constexpr (SP2) {
;             int tz_ = __builtin_amdgcn_readfirstlane(t | (ui > 0 ? 0 : 1)); asm volatile("" : "+s"(tz_));
;     ...
;         for (int a = 0; a < 2; ++a)
; #pragma unroll
;             for (int b = 0; b < 2; ++b)
; #pragma unroll
;                 for (int m = 0; m < 4; ++m)
; #pragma unroll
;                     for (int n = 0; n < 2; ++n) acc[a][b][m][n] = (f32x4){0.f, 0.f, 0.f, 0.f};
.LBB0_234:
	s_cmp_eq_u32 s16, 0
	s_cselect_b64 s[16:17], -1, 0
	s_add_u32 s57, s14, 0x100
	s_addc_u32 s62, s15, 0
	s_add_u32 s14, s12, 0xb0080
	s_addc_u32 s15, s13, 0
	v_mov_b32_e32 v2, 0
	v_cndmask_b32_e64 v248, 0, 1, s[16:17]
	s_and_b32 s101, s16, 1
	v_lshl_add_u64 v[222:223], s[14:15], 0, v[218:219]
	v_lshl_add_u64 v[224:225], s[14:15], 0, v[220:221]
	s_mov_b32 s63, -2
	s_mov_b64 s[14:15], 0
	v_mov_b32_e32 v3, v2
	v_mov_b64_e32 v[4:5], 0
	v_mov_b64_e32 v[6:7], 0
	v_mov_b64_e32 v[8:9], 0
	v_mov_b64_e32 v[10:11], 0
	v_mov_b64_e32 v[12:13], 0
	v_mov_b64_e32 v[14:15], 0
	v_mov_b64_e32 v[16:17], 0
	v_mov_b64_e32 v[18:19], 0
	v_mov_b64_e32 v[20:21], 0
	v_mov_b64_e32 v[22:23], 0
	v_mov_b64_e32 v[24:25], 0
	v_mov_b64_e32 v[26:27], 0
	v_mov_b64_e32 v[28:29], 0
	v_mov_b64_e32 v[30:31], 0
	v_mov_b64_e32 v[32:33], 0
	v_mov_b64_e32 v[34:35], 0
	v_mov_b64_e32 v[36:37], 0
	v_mov_b64_e32 v[38:39], 0
	v_mov_b64_e32 v[40:41], 0
	v_mov_b64_e32 v[42:43], 0
	v_mov_b64_e32 v[44:45], 0
	v_mov_b64_e32 v[46:47], 0
	v_mov_b64_e32 v[48:49], 0
	v_mov_b64_e32 v[50:51], 0
	v_mov_b64_e32 v[52:53], 0
	v_mov_b64_e32 v[54:55], 0
	v_mov_b64_e32 v[56:57], 0
	v_mov_b64_e32 v[58:59], 0
	v_mov_b64_e32 v[60:61], 0
	v_mov_b64_e32 v[62:63], 0
	v_mov_b64_e32 v[64:65], 0
	v_mov_b64_e32 v[66:67], 0
	v_mov_b64_e32 v[68:69], 0
	v_mov_b64_e32 v[70:71], 0
	v_mov_b64_e32 v[72:73], 0
	v_mov_b64_e32 v[74:75], 0
	v_mov_b64_e32 v[76:77], 0
	v_mov_b64_e32 v[78:79], 0
	v_mov_b64_e32 v[80:81], 0
	v_mov_b64_e32 v[82:83], 0
	v_mov_b64_e32 v[84:85], 0
	v_mov_b64_e32 v[86:87], 0
	v_mov_b64_e32 v[88:89], 0
	v_mov_b64_e32 v[90:91], 0
	v_mov_b64_e32 v[92:93], 0
	v_mov_b64_e32 v[94:95], 0
	v_mov_b64_e32 v[96:97], 0
	v_mov_b64_e32 v[98:99], 0
	v_mov_b64_e32 v[100:101], 0
	v_mov_b64_e32 v[102:103], 0
	v_mov_b64_e32 v[104:105], 0
	v_mov_b64_e32 v[106:107], 0
	v_mov_b64_e32 v[108:109], 0
	v_mov_b64_e32 v[110:111], 0
	v_mov_b64_e32 v[112:113], 0
	v_mov_b64_e32 v[114:115], 0
	v_mov_b64_e32 v[116:117], 0
	v_mov_b64_e32 v[118:119], 0
	v_mov_b64_e32 v[120:121], 0
	v_mov_b64_e32 v[122:123], 0
	v_mov_b64_e32 v[124:125], 0
	v_mov_b64_e32 v[126:127], 0
	v_mov_b64_e32 v[128:129], 0
	s_branch .LBB0_236

; #define PG8_STAGE(bufoff, gbase, voff) do { _Pragma("unroll") for (int _i = 0; _i < 2; ++_i) \
;         __builtin_amdgcn_global_load_lds((const unsigned*)((const char*)(gbase) + (voff)[_i]), (PG8_LAS unsigned*)(lds + (bufoff) + ldsw + _i * 8192), 16, 0, 0); } while (0)
; #define PG8_LDA(dst, b, h) do { _Pragma("unroll") for (int m = 0; m < 4; ++m) _Pragma("unroll") for (int k = 0; k < 2; ++k) dst[m][k] = *(const PG8_LAS bf16x8*)(lds + PG8_SA(b, h) + aoff + m * 2048 + k * 1024); } while (0)
; #define PG8_LDB(dst, b, h) do { _Pragma("unroll") for (int n = 0; n < 2; ++n) _Pragma("unroll") for (int k = 0; k < 2; ++k) dst[n][k] = *(const PG8_LAS bf16x8*)(lds + PG8_SB(b, h) + boff + n * 2048 + k * 1024); } while (0)
; #define PG8_MMA(ai, bj, At, Bt) do { __builtin_amdgcn_s_setprio(1); _Pragma("unroll") for (int m = 0; m < 4; ++m) _Pragma("unroll") for (int n = 0; n < 2; ++n) _Pragma("unroll") for (int k = 0; k < 2; ++k) \
;         acc[ai][bj][m][n] = __builtin_amdgcn_mfma_f32_16x16x32_bf16(Bt[n][k], At[m][k], acc[ai][bj][m][n], 0, 0, 0); __builtin_amdgcn_s_setprio(0); } while (0)
; #define PG8_WAIT_V(n) asm volatile("s_waitcnt vmcnt(" #n ")" ::: "memory")
; #define PG8_WAIT_VN(n) asm volatile("s_waitcnt vmcnt(%0)" :: "n"(n) : "memory")
; #define PG8_WAIT_L(n) asm volatile("s_waitcnt lgkmcnt(" #n ")" ::: "memory")
; #define PG8_BAR __builtin_amdgcn_s_barrier()
; #define PG8_SCHED __builtin_amdgcn_sched_barrier(0)
; template <class Epi, class Sched, bool ALIGN_EPI = false, bool SP2 = false>
; __device__ __forceinline__ void gemm_phase(PG8_LAS unsigned char* lds, const Gemm g, const Sched& S, const Epi& E, const int wave_id) {
;     ...
;             int tz_ = __builtin_amdgcn_readfirstlane(t | (ui > 0 ? 0 : 1)); asm volatile("" : "+s"(tz_));
;             const bool strict = !(Epi::NS > 0 && tz_ == 0);
;             PG8_LDB(B0, 0, 0); PG8_LDB(B1, 0, 1); PG8_SCHED; PG8_LDA(At, 0, 0); PG8_STAGE(PG8_SA(1, 1), a1 + hstep, voffA);
;             PG8_WAIT_VN(8 + Epi::NS); if (strict) PG8_WAIT_V(8); PG8_WAIT_L(0); PG8_BAR; PG8_MMA(0, 0, At, B0); PG8_MMA(0, 1, At, B1); PG8_BAR; PG8_SCHED;
.LBB0_236:
	v_add_u32_e32 v130, 0, v246
	v_add_u32_e32 v131, 0x10000, v130
	v_add_u32_e32 v142, 0x14000, v130
	ds_read_b128 v[146:149], v131
	ds_read_b128 v[150:153], v131 offset:1024
	ds_read_b128 v[154:157], v131 offset:2048
	ds_read_b128 v[158:161], v131 offset:3072
	ds_read_b128 v[130:133], v142
	ds_read_b128 v[134:137], v142 offset:1024
	ds_read_b128 v[138:141], v142 offset:2048
	ds_read_b128 v[142:145], v142 offset:3072
	v_lshl_add_u64 v[194:195], v[224:225], 0, s[14:15]
	s_add_i32 m0, s31, 0xc000
	ds_read_b128 v[186:189], v247
	ds_read_b128 v[190:193], v247 offset:1024
	ds_read_b128 v[178:181], v247 offset:2048
	ds_read_b128 v[182:185], v247 offset:3072
	ds_read_b128 v[170:173], v247 offset:4096
	ds_read_b128 v[174:177], v247 offset:5120
	ds_read_b128 v[162:165], v247 offset:6144
	ds_read_b128 v[166:169], v247 offset:7168
	global_load_lds_dwordx4 v[194:195], off
	v_lshl_add_u64 v[194:195], v[222:223], 0, s[14:15]
	s_add_i32 m0, s31, 0xe000
	s_add_i32 s16, s63, s101
	s_add_i32 s16, s16, 2
	s_mov_b32 s100, s16
	s_cmp_lg_u32 s16, 0
	global_load_lds_dwordx4 v[194:195], off
	s_waitcnt vmcnt(24)
	s_cselect_b64 s[20:21], -1, 0
	s_cmp_eq_u32 s16, 0
	s_cbranch_scc1 .LBB0_238
	s_waitcnt vmcnt(8)

; template <class Epi, class Sched, bool ALIGN_EPI = false, bool SP2 = false>
; __device__ __forceinline__ void gemm_phase(PG8_LAS unsigned char* lds, const Gemm g, const Sched& S, const Epi& E, const int wave_id) {
;     ...
;         const char* nA = has_next ? (const char*)g.A + (size_t)nxt.pm * tstep : cA; const char* nB = has_next ? (const char*)g.Bt + (size_t)nxt.pn * tstep : cB;
;         for (int t = 0; t < nt; t += 2) {
;             const bool last = (t == nt - 2);
;             const char* a1 = cA + (size_t)(t + 1) * kstep;
;             const char* a2 = last ? nA : cA + (size_t)(t + 2) * kstep; const char* b2 = last ? nB : cB + (size_t)(t + 2) * kstep;
;             const char* a3 = a2 + kstep; const char* b3 = b2 + kstep;
;             if (last && has_next) S.a_ready(nxt);
;             if constexpr (SP2) {
;             int tz_ = __builtin_amdgcn_readfirstlane(t | (ui > 0 ? 0 : 1)); asm volatile("" : "+s"(tz_));
;     ...
;         for (int a = 0; a < 2; ++a)
; #pragma unroll
;             for (int b = 0; b < 2; ++b)
; #pragma unroll
;                 for (int m = 0; m < 4; ++m)
; #pragma unroll
;                     for (int n = 0; n < 2; ++n) acc[a][b][m][n] = (f32x4){0.f, 0.f, 0.f, 0.f};
.LBB0_419:
	s_ashr_i32 s23, s22, 31
	s_lshl_b64 s[12:13], s[22:23], 19
	s_add_u32 s24, s54, s12
	s_addc_u32 s25, s55, s13
	s_and_b64 s[12:13], s[6:7], exec
	s_cselect_b32 s23, s25, s9
	s_cselect_b32 s29, s24, s8
	s_ashr_i32 s21, s20, 31
	s_lshl_b64 s[12:13], s[20:21], 19
	s_add_u32 s26, s67, s12
	s_addc_u32 s27, s74, s13
	s_and_b64 s[12:13], s[6:7], exec
	s_cselect_b32 s21, s27, s11
	s_cselect_b32 s31, s26, s10
	s_cmp_eq_u32 s14, 0
	s_cselect_b64 s[12:13], -1, 0
	s_add_u32 s36, s10, 0x100
	s_addc_u32 s37, s11, 0
	s_add_u32 s10, s8, 0x40080
	s_addc_u32 s11, s9, 0
	v_mov_b32_e32 v2, 0
	v_cndmask_b32_e64 v248, 0, 1, s[12:13]
	s_and_b32 s101, s12, 1
	v_lshl_add_u64 v[222:223], s[10:11], 0, v[218:219]
	v_lshl_add_u64 v[224:225], s[10:11], 0, v[220:221]
	s_mov_b32 s40, -2
	s_mov_b64 s[10:11], 0
	v_mov_b32_e32 v3, v2
	v_mov_b64_e32 v[4:5], 0
	v_mov_b64_e32 v[6:7], 0
	v_mov_b64_e32 v[8:9], 0
	v_mov_b64_e32 v[10:11], 0
	v_mov_b64_e32 v[12:13], 0
	v_mov_b64_e32 v[14:15], 0
	v_mov_b64_e32 v[16:17], 0
	v_mov_b64_e32 v[18:19], 0
	v_mov_b64_e32 v[20:21], 0
	v_mov_b64_e32 v[22:23], 0
	v_mov_b64_e32 v[24:25], 0
	v_mov_b64_e32 v[26:27], 0
	v_mov_b64_e32 v[28:29], 0
	v_mov_b64_e32 v[30:31], 0
	v_mov_b64_e32 v[32:33], 0
	v_mov_b64_e32 v[34:35], 0
	v_mov_b64_e32 v[36:37], 0
	v_mov_b64_e32 v[38:39], 0
	v_mov_b64_e32 v[40:41], 0
	v_mov_b64_e32 v[42:43], 0
	v_mov_b64_e32 v[44:45], 0
	v_mov_b64_e32 v[46:47], 0
	v_mov_b64_e32 v[48:49], 0
	v_mov_b64_e32 v[50:51], 0
	v_mov_b64_e32 v[52:53], 0
	v_mov_b64_e32 v[54:55], 0
	v_mov_b64_e32 v[56:57], 0
	v_mov_b64_e32 v[58:59], 0
	v_mov_b64_e32 v[60:61], 0
	v_mov_b64_e32 v[62:63], 0
	v_mov_b64_e32 v[64:65], 0
	v_mov_b64_e32 v[66:67], 0
	v_mov_b64_e32 v[68:69], 0
	v_mov_b64_e32 v[70:71], 0
	v_mov_b64_e32 v[72:73], 0
	v_mov_b64_e32 v[74:75], 0
	v_mov_b64_e32 v[76:77], 0
	v_mov_b64_e32 v[78:79], 0
	v_mov_b64_e32 v[80:81], 0
	v_mov_b64_e32 v[82:83], 0
	v_mov_b64_e32 v[84:85], 0
	v_mov_b64_e32 v[86:87], 0
	v_mov_b64_e32 v[88:89], 0
	v_mov_b64_e32 v[90:91], 0
	v_mov_b64_e32 v[92:93], 0
	v_mov_b64_e32 v[94:95], 0
	v_mov_b64_e32 v[96:97], 0
	v_mov_b64_e32 v[98:99], 0
	v_mov_b64_e32 v[100:101], 0
	v_mov_b64_e32 v[102:103], 0
	v_mov_b64_e32 v[104:105], 0
	v_mov_b64_e32 v[106:107], 0
	v_mov_b64_e32 v[108:109], 0
	v_mov_b64_e32 v[110:111], 0
	v_mov_b64_e32 v[112:113], 0
	v_mov_b64_e32 v[114:115], 0
	v_mov_b64_e32 v[116:117], 0
	v_mov_b64_e32 v[118:119], 0
	v_mov_b64_e32 v[120:121], 0
	v_mov_b64_e32 v[122:123], 0
	v_mov_b64_e32 v[124:125], 0
	v_mov_b64_e32 v[126:127], 0
	v_mov_b64_e32 v[128:129], 0
	s_branch .LBB0_421

; #define PG8_STAGE(bufoff, gbase, voff) do { _Pragma("unroll") for (int _i = 0; _i < 2; ++_i) \
;         __builtin_amdgcn_global_load_lds((const unsigned*)((const char*)(gbase) + (voff)[_i]), (PG8_LAS unsigned*)(lds + (bufoff) + ldsw + _i * 8192), 16, 0, 0); } while (0)
; #define PG8_LDA(dst, b, h) do { _Pragma("unroll") for (int m = 0; m < 4; ++m) _Pragma("unroll") for (int k = 0; k < 2; ++k) dst[m][k] = *(const PG8_LAS bf16x8*)(lds + PG8_SA(b, h) + aoff + m * 2048 + k * 1024); } while (0)
; #define PG8_LDB(dst, b, h) do { _Pragma("unroll") for (int n = 0; n < 2; ++n) _Pragma("unroll") for (int k = 0; k < 2; ++k) dst[n][k] = *(const PG8_LAS bf16x8*)(lds + PG8_SB(b, h) + boff + n * 2048 + k * 1024); } while (0)
; #define PG8_MMA(ai, bj, At, Bt) do { __builtin_amdgcn_s_setprio(1); _Pragma("unroll") for (int m = 0; m < 4; ++m) _Pragma("unroll") for (int n = 0; n < 2; ++n) _Pragma("unroll") for (int k = 0; k < 2; ++k) \
;         acc[ai][bj][m][n] = __builtin_amdgcn_mfma_f32_16x16x32_bf16(Bt[n][k], At[m][k], acc[ai][bj][m][n], 0, 0, 0); __builtin_amdgcn_s_setprio(0); } while (0)
; #define PG8_WAIT_V(n) asm volatile("s_waitcnt vmcnt(" #n ")" ::: "memory")
; #define PG8_WAIT_VN(n) asm volatile("s_waitcnt vmcnt(%0)" :: "n"(n) : "memory")
; #define PG8_WAIT_L(n) asm volatile("s_waitcnt lgkmcnt(" #n ")" ::: "memory")
; #define PG8_BAR __builtin_amdgcn_s_barrier()
; #define PG8_SCHED __builtin_amdgcn_sched_barrier(0)
; template <class Epi, class Sched, bool ALIGN_EPI = false, bool SP2 = false>
; __device__ __forceinline__ void gemm_phase(PG8_LAS unsigned char* lds, const Gemm g, const Sched& S, const Epi& E, const int wave_id) {
;     ...
;             int tz_ = __builtin_amdgcn_readfirstlane(t | (ui > 0 ? 0 : 1)); asm volatile("" : "+s"(tz_));
;             const bool strict = !(Epi::NS > 0 && tz_ == 0);
;             PG8_LDB(B0, 0, 0); PG8_LDB(B1, 0, 1); PG8_SCHED; PG8_LDA(At, 0, 0); PG8_STAGE(PG8_SA(1, 1), a1 + hstep, voffA);
;             PG8_WAIT_VN(8 + Epi::NS); if (strict) PG8_WAIT_V(8); PG8_WAIT_L(0); PG8_BAR; PG8_MMA(0, 0, At, B0); PG8_MMA(0, 1, At, B1); PG8_BAR; PG8_SCHED;
.LBB0_421:
	s_waitcnt lgkmcnt(0)
	v_add_u32_e32 v130, 0, v246
	v_add_u32_e32 v131, 0x10000, v130
	v_add_u32_e32 v142, 0x14000, v130
	ds_read_b128 v[146:149], v131
	ds_read_b128 v[150:153], v131 offset:1024
	ds_read_b128 v[154:157], v131 offset:2048
	ds_read_b128 v[158:161], v131 offset:3072
	ds_read_b128 v[130:133], v142
	ds_read_b128 v[134:137], v142 offset:1024
	ds_read_b128 v[138:141], v142 offset:2048
	ds_read_b128 v[142:145], v142 offset:3072
	v_lshl_add_u64 v[194:195], v[224:225], 0, s[10:11]
	s_add_i32 m0, s91, 0xc000
	ds_read_b128 v[186:189], v247
	ds_read_b128 v[190:193], v247 offset:1024
	ds_read_b128 v[178:181], v247 offset:2048
	ds_read_b128 v[182:185], v247 offset:3072
	ds_read_b128 v[170:173], v247 offset:4096
	ds_read_b128 v[174:177], v247 offset:5120
	ds_read_b128 v[162:165], v247 offset:6144
	ds_read_b128 v[166:169], v247 offset:7168
	global_load_lds_dwordx4 v[194:195], off
	v_lshl_add_u64 v[194:195], v[222:223], 0, s[10:11]
	s_add_i32 m0, s91, 0xe000
	s_add_i32 s12, s40, s101
	s_add_i32 s12, s12, 2
	s_mov_b32 s100, s12
	s_cmp_lg_u32 s12, 0
	global_load_lds_dwordx4 v[194:195], off
	s_waitcnt vmcnt(24)
	s_cselect_b64 s[34:35], -1, 0
	s_cmp_eq_u32 s12, 0
	s_cbranch_scc1 .LBB0_423
	s_waitcnt vmcnt(8)

; template <class Epi, class Sched, bool ALIGN_EPI = false, bool SP2 = false>
; __device__ __forceinline__ void gemm_phase(PG8_LAS unsigned char* lds, const Gemm g, const Sched& S, const Epi& E, const int wave_id) {
;     ...
;         const char* nA = has_next ? (const char*)g.A + (size_t)nxt.pm * tstep : cA; const char* nB = has_next ? (const char*)g.Bt + (size_t)nxt.pn * tstep : cB;
;         for (int t = 0; t < nt; t += 2) {
;             const bool last = (t == nt - 2);
;             const char* a1 = cA + (size_t)(t + 1) * kstep;
;             const char* a2 = last ? nA : cA + (size_t)(t + 2) * kstep; const char* b2 = last ? nB : cB + (size_t)(t + 2) * kstep;
;             const char* a3 = a2 + kstep; const char* b3 = b2 + kstep;
;             if (last && has_next) S.a_ready(nxt);
;             if constexpr (SP2) {
;             int tz_ = __builtin_amdgcn_readfirstlane(t | (ui > 0 ? 0 : 1)); asm volatile("" : "+s"(tz_));
;     ...
;         for (int a = 0; a < 2; ++a)
; #pragma unroll
;             for (int b = 0; b < 2; ++b)
; #pragma unroll
;                 for (int m = 0; m < 4; ++m)
; #pragma unroll
;                     for (int n = 0; n < 2; ++n) acc[a][b][m][n] = (f32x4){0.f, 0.f, 0.f, 0.f};
.LBB0_1820:
	s_ashr_i32 s11, s10, 31
	s_lshl_b64 s[12:13], s[10:11], 19
	s_add_u32 s12, s31, s12
	s_addc_u32 s13, s34, s13
	s_and_b64 s[14:15], s[6:7], exec
	s_cselect_b32 s11, s13, s19
	s_cselect_b32 s63, s12, s18
	s_ashr_i32 s9, s8, 31
	s_lshl_b64 s[14:15], s[8:9], 19
	s_add_u32 s14, s35, s14
	s_addc_u32 s15, s36, s15
	s_and_b64 s[24:25], s[6:7], exec
	s_cselect_b32 s9, s15, s21
	s_cselect_b32 s67, s14, s20
	s_cmp_eq_u32 s22, 0
	s_cselect_b64 s[22:23], -1, 0
	s_add_u32 s68, s20, 0x100
	s_addc_u32 s69, s21, 0
	s_add_u32 s20, s18, 0x40080
	s_addc_u32 s21, s19, 0
	v_mov_b32_e32 v2, 0
	v_cndmask_b32_e64 v248, 0, 1, s[22:23]
	s_and_b32 s101, s22, 1
	v_lshl_add_u64 v[222:223], s[20:21], 0, v[218:219]
	v_lshl_add_u64 v[224:225], s[20:21], 0, v[220:221]
	s_mov_b32 s74, -2
	s_mov_b64 s[20:21], 0
	v_mov_b32_e32 v3, v2
	v_mov_b64_e32 v[4:5], 0
	v_mov_b64_e32 v[6:7], 0
	v_mov_b64_e32 v[8:9], 0
	v_mov_b64_e32 v[10:11], 0
	v_mov_b64_e32 v[12:13], 0
	v_mov_b64_e32 v[14:15], 0
	v_mov_b64_e32 v[16:17], 0
	v_mov_b64_e32 v[18:19], 0
	v_mov_b64_e32 v[20:21], 0
	v_mov_b64_e32 v[22:23], 0
	v_mov_b64_e32 v[24:25], 0
	v_mov_b64_e32 v[26:27], 0
	v_mov_b64_e32 v[28:29], 0
	v_mov_b64_e32 v[30:31], 0
	v_mov_b64_e32 v[32:33], 0
	v_mov_b64_e32 v[34:35], 0
	v_mov_b64_e32 v[36:37], 0
	v_mov_b64_e32 v[38:39], 0
	v_mov_b64_e32 v[40:41], 0
	v_mov_b64_e32 v[42:43], 0
	v_mov_b64_e32 v[44:45], 0
	v_mov_b64_e32 v[46:47], 0
	v_mov_b64_e32 v[48:49], 0
	v_mov_b64_e32 v[50:51], 0
	v_mov_b64_e32 v[52:53], 0
	v_mov_b64_e32 v[54:55], 0
	v_mov_b64_e32 v[56:57], 0
	v_mov_b64_e32 v[58:59], 0
	v_mov_b64_e32 v[60:61], 0
	v_mov_b64_e32 v[62:63], 0
	v_mov_b64_e32 v[64:65], 0
	v_mov_b64_e32 v[66:67], 0
	v_mov_b64_e32 v[68:69], 0
	v_mov_b64_e32 v[70:71], 0
	v_mov_b64_e32 v[72:73], 0
	v_mov_b64_e32 v[74:75], 0
	v_mov_b64_e32 v[76:77], 0
	v_mov_b64_e32 v[78:79], 0
	v_mov_b64_e32 v[80:81], 0
	v_mov_b64_e32 v[82:83], 0
	v_mov_b64_e32 v[84:85], 0
	v_mov_b64_e32 v[86:87], 0
	v_mov_b64_e32 v[88:89], 0
	v_mov_b64_e32 v[90:91], 0
	v_mov_b64_e32 v[92:93], 0
	v_mov_b64_e32 v[94:95], 0
	v_mov_b64_e32 v[96:97], 0
	v_mov_b64_e32 v[98:99], 0
	v_mov_b64_e32 v[100:101], 0
	v_mov_b64_e32 v[102:103], 0
	v_mov_b64_e32 v[104:105], 0
	v_mov_b64_e32 v[106:107], 0
	v_mov_b64_e32 v[108:109], 0
	v_mov_b64_e32 v[110:111], 0
	v_mov_b64_e32 v[112:113], 0
	v_mov_b64_e32 v[114:115], 0
	v_mov_b64_e32 v[116:117], 0
	v_mov_b64_e32 v[118:119], 0
	v_mov_b64_e32 v[120:121], 0
	v_mov_b64_e32 v[122:123], 0
	v_mov_b64_e32 v[124:125], 0
	v_mov_b64_e32 v[126:127], 0
	v_mov_b64_e32 v[128:129], 0
	s_branch .LBB0_1822

; #define PG8_STAGE(bufoff, gbase, voff) do { _Pragma("unroll") for (int _i = 0; _i < 2; ++_i) \
;         __builtin_amdgcn_global_load_lds((const unsigned*)((const char*)(gbase) + (voff)[_i]), (PG8_LAS unsigned*)(lds + (bufoff) + ldsw + _i * 8192), 16, 0, 0); } while (0)
; #define PG8_LDA(dst, b, h) do { _Pragma("unroll") for (int m = 0; m < 4; ++m) _Pragma("unroll") for (int k = 0; k < 2; ++k) dst[m][k] = *(const PG8_LAS bf16x8*)(lds + PG8_SA(b, h) + aoff + m * 2048 + k * 1024); } while (0)
; #define PG8_LDB(dst, b, h) do { _Pragma("unroll") for (int n = 0; n < 2; ++n) _Pragma("unroll") for (int k = 0; k < 2; ++k) dst[n][k] = *(const PG8_LAS bf16x8*)(lds + PG8_SB(b, h) + boff + n * 2048 + k * 1024); } while (0)
; #define PG8_MMA(ai, bj, At, Bt) do { __builtin_amdgcn_s_setprio(1); _Pragma("unroll") for (int m = 0; m < 4; ++m) _Pragma("unroll") for (int n = 0; n < 2; ++n) _Pragma("unroll") for (int k = 0; k < 2; ++k) \
;         acc[ai][bj][m][n] = __builtin_amdgcn_mfma_f32_16x16x32_bf16(Bt[n][k], At[m][k], acc[ai][bj][m][n], 0, 0, 0); __builtin_amdgcn_s_setprio(0); } while (0)
; #define PG8_WAIT_V(n) asm volatile("s_waitcnt vmcnt(" #n ")" ::: "memory")
; #define PG8_WAIT_VN(n) asm volatile("s_waitcnt vmcnt(%0)" :: "n"(n) : "memory")
; #define PG8_WAIT_L(n) asm volatile("s_waitcnt lgkmcnt(" #n ")" ::: "memory")
; #define PG8_BAR __builtin_amdgcn_s_barrier()
; #define PG8_SCHED __builtin_amdgcn_sched_barrier(0)
; template <class Epi, class Sched, bool ALIGN_EPI = false, bool SP2 = false>
; __device__ __forceinline__ void gemm_phase(PG8_LAS unsigned char* lds, const Gemm g, const Sched& S, const Epi& E, const int wave_id) {
;     ...
;             int tz_ = __builtin_amdgcn_readfirstlane(t | (ui > 0 ? 0 : 1)); asm volatile("" : "+s"(tz_));
;             const bool strict = !(Epi::NS > 0 && tz_ == 0);
;             PG8_LDB(B0, 0, 0); PG8_LDB(B1, 0, 1); PG8_SCHED; PG8_LDA(At, 0, 0); PG8_STAGE(PG8_SA(1, 1), a1 + hstep, voffA);
;             PG8_WAIT_VN(8 + Epi::NS); if (strict) PG8_WAIT_V(8); PG8_WAIT_L(0); PG8_BAR; PG8_MMA(0, 0, At, B0); PG8_MMA(0, 1, At, B1); PG8_BAR; PG8_SCHED;
.LBB0_1822:
	v_add_u32_e32 v130, 0, v246
	v_add_u32_e32 v131, 0x10000, v130
	v_add_u32_e32 v142, 0x14000, v130
	ds_read_b128 v[146:149], v131
	ds_read_b128 v[150:153], v131 offset:1024
	ds_read_b128 v[154:157], v131 offset:2048
	ds_read_b128 v[158:161], v131 offset:3072
	ds_read_b128 v[130:133], v142
	ds_read_b128 v[134:137], v142 offset:1024
	ds_read_b128 v[138:141], v142 offset:2048
	ds_read_b128 v[142:145], v142 offset:3072
	v_lshl_add_u64 v[194:195], v[224:225], 0, s[20:21]
	s_add_i32 m0, s39, 0xc000
	ds_read_b128 v[186:189], v247
	ds_read_b128 v[190:193], v247 offset:1024
	ds_read_b128 v[178:181], v247 offset:2048
	ds_read_b128 v[182:185], v247 offset:3072
	ds_read_b128 v[170:173], v247 offset:4096
	ds_read_b128 v[174:177], v247 offset:5120
	ds_read_b128 v[162:165], v247 offset:6144
	ds_read_b128 v[166:169], v247 offset:7168
	global_load_lds_dwordx4 v[194:195], off
	v_lshl_add_u64 v[194:195], v[222:223], 0, s[20:21]
	s_add_i32 m0, s39, 0xe000
	s_add_i32 s22, s74, s101
	s_add_i32 s22, s22, 2
	s_mov_b32 s100, s22
	s_cmp_lg_u32 s22, 0
	global_load_lds_dwordx4 v[194:195], off
	s_waitcnt vmcnt(24)
	s_cselect_b64 s[26:27], -1, 0
	s_cmp_eq_u32 s22, 0
	s_cbranch_scc1 .LBB0_1824
	s_waitcnt vmcnt(8)

; template <class Epi, class Sched, bool ALIGN_EPI = false, bool SP2 = false>
; __device__ __forceinline__ void gemm_phase(PG8_LAS unsigned char* lds, const Gemm g, const Sched& S, const Epi& E, const int wave_id) {
;     ...
;         const char* nA = has_next ? (const char*)g.A + (size_t)nxt.pm * tstep : cA; const char* nB = has_next ? (const char*)g.Bt + (size_t)nxt.pn * tstep : cB;
;         for (int t = 0; t < nt; t += 2) {
;             const bool last = (t == nt - 2);
;             const char* a1 = cA + (size_t)(t + 1) * kstep;
;             const char* a2 = last ? nA : cA + (size_t)(t + 2) * kstep; const char* b2 = last ? nB : cB + (size_t)(t + 2) * kstep;
;             const char* a3 = a2 + kstep; const char* b3 = b2 + kstep;
;             if (last && has_next) S.a_ready(nxt);
;             if constexpr (SP2) {
;             int tz_ = __builtin_amdgcn_readfirstlane(t | (ui > 0 ? 0 : 1)); asm volatile("" : "+s"(tz_));
;     ...
;         for (int a = 0; a < 2; ++a)
; #pragma unroll
;             for (int b = 0; b < 2; ++b)
; #pragma unroll
;                 for (int m = 0; m < 4; ++m)
; #pragma unroll
;                     for (int n = 0; n < 2; ++n) acc[a][b][m][n] = (f32x4){0.f, 0.f, 0.f, 0.f};
.LBB0_1951:
	s_ashr_i32 s13, s12, 31
	s_lshl_b64 s[14:15], s[12:13], 19
	s_add_u32 s14, s34, s14
	s_addc_u32 s15, s35, s15
	s_and_b64 s[16:17], s[6:7], exec
	s_cselect_b32 s13, s15, s21
	s_cselect_b32 s68, s14, s20
	s_ashr_i32 s11, s10, 31
	s_lshl_b64 s[16:17], s[10:11], 19
	s_add_u32 s16, s36, s16
	s_addc_u32 s17, s37, s17
	s_and_b64 s[26:27], s[6:7], exec
	s_cselect_b32 s11, s17, s23
	s_cselect_b32 s69, s16, s22
	s_cmp_eq_u32 s24, 0
	s_cselect_b64 s[24:25], -1, 0
	s_add_u32 s74, s22, 0x100
	s_addc_u32 s75, s23, 0
	s_add_u32 s22, s20, 0x40080
	s_addc_u32 s23, s21, 0
	v_mov_b32_e32 v2, 0
	v_cndmask_b32_e64 v248, 0, 1, s[24:25]
	s_and_b32 s101, s24, 1
	v_lshl_add_u64 v[222:223], s[22:23], 0, v[218:219]
	v_lshl_add_u64 v[224:225], s[22:23], 0, v[220:221]
	s_mov_b32 s76, -2
	s_mov_b64 s[22:23], 0
	v_mov_b32_e32 v3, v2
	v_mov_b64_e32 v[4:5], 0
	v_mov_b64_e32 v[6:7], 0
	v_mov_b64_e32 v[8:9], 0
	v_mov_b64_e32 v[10:11], 0
	v_mov_b64_e32 v[12:13], 0
	v_mov_b64_e32 v[14:15], 0
	v_mov_b64_e32 v[16:17], 0
	v_mov_b64_e32 v[18:19], 0
	v_mov_b64_e32 v[20:21], 0
	v_mov_b64_e32 v[22:23], 0
	v_mov_b64_e32 v[24:25], 0
	v_mov_b64_e32 v[26:27], 0
	v_mov_b64_e32 v[28:29], 0
	v_mov_b64_e32 v[30:31], 0
	v_mov_b64_e32 v[32:33], 0
	v_mov_b64_e32 v[34:35], 0
	v_mov_b64_e32 v[36:37], 0
	v_mov_b64_e32 v[38:39], 0
	v_mov_b64_e32 v[40:41], 0
	v_mov_b64_e32 v[42:43], 0
	v_mov_b64_e32 v[44:45], 0
	v_mov_b64_e32 v[46:47], 0
	v_mov_b64_e32 v[48:49], 0
	v_mov_b64_e32 v[50:51], 0
	v_mov_b64_e32 v[52:53], 0
	v_mov_b64_e32 v[54:55], 0
	v_mov_b64_e32 v[56:57], 0
	v_mov_b64_e32 v[58:59], 0
	v_mov_b64_e32 v[60:61], 0
	v_mov_b64_e32 v[62:63], 0
	v_mov_b64_e32 v[64:65], 0
	v_mov_b64_e32 v[66:67], 0
	v_mov_b64_e32 v[68:69], 0
	v_mov_b64_e32 v[70:71], 0
	v_mov_b64_e32 v[72:73], 0
	v_mov_b64_e32 v[74:75], 0
	v_mov_b64_e32 v[76:77], 0
	v_mov_b64_e32 v[78:79], 0
	v_mov_b64_e32 v[80:81], 0
	v_mov_b64_e32 v[82:83], 0
	v_mov_b64_e32 v[84:85], 0
	v_mov_b64_e32 v[86:87], 0
	v_mov_b64_e32 v[88:89], 0
	v_mov_b64_e32 v[90:91], 0
	v_mov_b64_e32 v[92:93], 0
	v_mov_b64_e32 v[94:95], 0
	v_mov_b64_e32 v[96:97], 0
	v_mov_b64_e32 v[98:99], 0
	v_mov_b64_e32 v[100:101], 0
	v_mov_b64_e32 v[102:103], 0
	v_mov_b64_e32 v[104:105], 0
	v_mov_b64_e32 v[106:107], 0
	v_mov_b64_e32 v[108:109], 0
	v_mov_b64_e32 v[110:111], 0
	v_mov_b64_e32 v[112:113], 0
	v_mov_b64_e32 v[114:115], 0
	v_mov_b64_e32 v[116:117], 0
	v_mov_b64_e32 v[118:119], 0
	v_mov_b64_e32 v[120:121], 0
	v_mov_b64_e32 v[122:123], 0
	v_mov_b64_e32 v[124:125], 0
	v_mov_b64_e32 v[126:127], 0
	v_mov_b64_e32 v[128:129], 0
	s_branch .LBB0_1953

; #define PG8_STAGE(bufoff, gbase, voff) do { _Pragma("unroll") for (int _i = 0; _i < 2; ++_i) \
;         __builtin_amdgcn_global_load_lds((const unsigned*)((const char*)(gbase) + (voff)[_i]), (PG8_LAS unsigned*)(lds + (bufoff) + ldsw + _i * 8192), 16, 0, 0); } while (0)
; #define PG8_LDA(dst, b, h) do { _Pragma("unroll") for (int m = 0; m < 4; ++m) _Pragma("unroll") for (int k = 0; k < 2; ++k) dst[m][k] = *(const PG8_LAS bf16x8*)(lds + PG8_SA(b, h) + aoff + m * 2048 + k * 1024); } while (0)
; #define PG8_LDB(dst, b, h) do { _Pragma("unroll") for (int n = 0; n < 2; ++n) _Pragma("unroll") for (int k = 0; k < 2; ++k) dst[n][k] = *(const PG8_LAS bf16x8*)(lds + PG8_SB(b, h) + boff + n * 2048 + k * 1024); } while (0)
; #define PG8_MMA(ai, bj, At, Bt) do { __builtin_amdgcn_s_setprio(1); _Pragma("unroll") for (int m = 0; m < 4; ++m) _Pragma("unroll") for (int n = 0; n < 2; ++n) _Pragma("unroll") for (int k = 0; k < 2; ++k) \
;         acc[ai][bj][m][n] = __builtin_amdgcn_mfma_f32_16x16x32_bf16(Bt[n][k], At[m][k], acc[ai][bj][m][n], 0, 0, 0); __builtin_amdgcn_s_setprio(0); } while (0)
; #define PG8_WAIT_V(n) asm volatile("s_waitcnt vmcnt(" #n ")" ::: "memory")
; #define PG8_WAIT_VN(n) asm volatile("s_waitcnt vmcnt(%0)" :: "n"(n) : "memory")
; #define PG8_WAIT_L(n) asm volatile("s_waitcnt lgkmcnt(" #n ")" ::: "memory")
; #define PG8_BAR __builtin_amdgcn_s_barrier()
; #define PG8_SCHED __builtin_amdgcn_sched_barrier(0)
; template <class Epi, class Sched, bool ALIGN_EPI = false, bool SP2 = false>
; __device__ __forceinline__ void gemm_phase(PG8_LAS unsigned char* lds, const Gemm g, const Sched& S, const Epi& E, const int wave_id) {
;     ...
;             int tz_ = __builtin_amdgcn_readfirstlane(t | (ui > 0 ? 0 : 1)); asm volatile("" : "+s"(tz_));
;             const bool strict = !(Epi::NS > 0 && tz_ == 0);
;             PG8_LDB(B0, 0, 0); PG8_LDB(B1, 0, 1); PG8_SCHED; PG8_LDA(At, 0, 0); PG8_STAGE(PG8_SA(1, 1), a1 + hstep, voffA);
;             PG8_WAIT_VN(8 + Epi::NS); if (strict) PG8_WAIT_V(8); PG8_WAIT_L(0); PG8_BAR; PG8_MMA(0, 0, At, B0); PG8_MMA(0, 1, At, B1); PG8_BAR; PG8_SCHED;
.LBB0_1953:
	v_add_u32_e32 v130, 0, v246
	v_add_u32_e32 v131, 0x10000, v130
	v_add_u32_e32 v142, 0x14000, v130
	ds_read_b128 v[146:149], v131
	ds_read_b128 v[150:153], v131 offset:1024
	ds_read_b128 v[154:157], v131 offset:2048
	ds_read_b128 v[158:161], v131 offset:3072
	ds_read_b128 v[130:133], v142
	ds_read_b128 v[134:137], v142 offset:1024
	ds_read_b128 v[138:141], v142 offset:2048
	ds_read_b128 v[142:145], v142 offset:3072
	v_lshl_add_u64 v[194:195], v[224:225], 0, s[22:23]
	s_add_i32 m0, s41, 0xc000
	ds_read_b128 v[186:189], v247
	ds_read_b128 v[190:193], v247 offset:1024
	ds_read_b128 v[178:181], v247 offset:2048
	ds_read_b128 v[182:185], v247 offset:3072
	ds_read_b128 v[170:173], v247 offset:4096
	ds_read_b128 v[174:177], v247 offset:5120
	ds_read_b128 v[162:165], v247 offset:6144
	ds_read_b128 v[166:169], v247 offset:7168
	global_load_lds_dwordx4 v[194:195], off
	v_lshl_add_u64 v[194:195], v[222:223], 0, s[22:23]
	s_add_i32 m0, s41, 0xe000
	s_add_i32 s24, s76, s101
	s_add_i32 s24, s24, 2
	s_mov_b32 s100, s24
	s_cmp_lg_u32 s24, 0
	global_load_lds_dwordx4 v[194:195], off
	s_waitcnt vmcnt(16)
	s_cselect_b64 s[28:29], -1, 0
	s_cmp_eq_u32 s24, 0
	s_cbranch_scc1 .LBB0_1955
	s_waitcnt vmcnt(8)
